# adds: attention Q-fragment wait and validity selects moved behind the item barrier (third Q fragment in its own registers); LN2 next-row bf16 unpack deferred behind the row reductions
# speedup vs baseline: 1.0256x; 1.0087x over previous
.LBB0_1248:
	v_lshlrev_b32_e32 v190, 6, v52
	v_ashrrev_i32_e32 v191, 31, v190
	v_lshlrev_b64 v[56:57], 1, v[190:191]
	v_lshl_add_u64 v[52:53], s[8:9], 0, v[56:57]
	v_and_b32_e32 v50, 48, v208
	v_ashrrev_i32_e32 v55, 31, v54
	v_lshl_add_u64 v[52:53], v[52:53], 0, v[50:51]
	v_lshlrev_b64 v[54:55], 12, v[54:55]
	v_lshl_add_u64 v[54:55], v[52:53], 0, v[54:55]
	global_load_dwordx4 v[74:77], v[54:55], off nt
	global_load_dwordx4 v[78:81], v[54:55], off offset:64 nt
	v_or3_b32 v54, v206, s20, 16
	v_cmp_gt_i32_e32 vcc, s24, v54
	v_mov_b32_e32 v82, s21
	s_and_b32 s16, s27, 1
	v_cndmask_b32_e32 v54, 0, v54, vcc
	v_add_u32_e32 v54, s17, v54
	v_cndmask_b32_e64 v54, v82, v54, s[66:67]
	v_ashrrev_i32_e32 v55, 31, v54
	v_lshlrev_b64 v[54:55], 12, v[54:55]
	v_lshl_add_u64 v[58:59], v[52:53], 0, v[54:55]
	global_load_dwordx4 v[220:223], v[58:59], off nt
	s_mul_i32 s0, s16, 0xae00
	v_bfe_u32 v161, v208, 3, 3
	s_add_i32 s88, s0, 0
	s_and_b64 s[0:1], s[66:67], vcc
	v_or_b32_e32 v83, s20, v161
	s_movk_i32 s34, 0x80f
	v_cmp_lt_i32_e64 s[74:75], s34, v83
	v_mov_b32_e32 v195, v51
	global_load_dwordx4 v[86:89], v[58:59], off offset:64 nt
	v_add_u32_e32 v50, s88, v50
	s_mov_b32 s86, s84
	s_mov_b32 s87, s84
	v_readlane_b32 s82, v254, 53
	s_mov_b32 s85, s84
	v_mov_b64_e32 v[112:113], s[86:87]
	v_readlane_b32 s83, v254, 54
	v_mov_b64_e32 v[110:111], s[84:85]
	s_andn2_b64 vcc, exec, s[66:67]
	v_lshlrev_b32_e32 v54, 4, v208
	v_and_b32_e32 v194, 0x70, v54
	v_cndmask_b32_e64 v54, v83, 0, s[74:75]
	v_add_u32_e32 v54, s17, v54
	v_or_b32_e32 v55, s21, v161
	v_cndmask_b32_e64 v54, v55, v54, s[66:67]
	v_lshl_add_u64 v[52:53], s[14:15], 0, v[56:57]
	v_ashrrev_i32_e32 v55, 31, v54
	v_lshl_add_u64 v[52:53], v[52:53], 0, v[194:195]
	v_lshlrev_b64 v[192:193], 12, v[54:55]
	v_lshl_add_u64 v[54:55], v[52:53], 0, v[192:193]
	global_load_dwordx4 v[66:69], v[54:55], off nt
	v_or_b32_e32 v54, 8, v83
	v_cmp_gt_i32_e64 s[72:73], s24, v54
	s_nop 1
	v_cndmask_b32_e64 v54, 0, v54, s[72:73]
	v_add_u32_e32 v54, s17, v54
	v_cndmask_b32_e64 v54, v82, v54, s[66:67]
	v_ashrrev_i32_e32 v55, 31, v54
	v_lshlrev_b64 v[188:189], 12, v[54:55]
	v_lshl_add_u64 v[54:55], v[52:53], 0, v[188:189]
	global_load_dwordx4 v[62:65], v[54:55], off nt
	v_or_b32_e32 v54, 16, v83
	v_cmp_gt_i32_e64 s[70:71], s24, v54
	s_nop 1
	v_cndmask_b32_e64 v54, 0, v54, s[70:71]
	v_add_u32_e32 v54, s17, v54
	v_cndmask_b32_e64 v54, v82, v54, s[66:67]
	v_ashrrev_i32_e32 v55, 31, v54
	v_lshlrev_b64 v[186:187], 12, v[54:55]
	v_lshl_add_u64 v[54:55], v[52:53], 0, v[186:187]
	global_load_dwordx4 v[58:61], v[54:55], off nt
	v_or_b32_e32 v54, 24, v83
	v_cmp_gt_i32_e64 s[68:69], s24, v54
	s_nop 1
	v_cndmask_b32_e64 v54, 0, v54, s[68:69]
	v_add_u32_e32 v54, s17, v54
	v_cndmask_b32_e64 v54, v82, v54, s[66:67]
	v_ashrrev_i32_e32 v55, 31, v54
	v_lshlrev_b64 v[184:185], 12, v[54:55]
	v_lshl_add_u64 v[52:53], v[52:53], 0, v[184:185]
	global_load_dwordx4 v[54:57], v[52:53], off nt
	v_mad_u32_u24 v52, v206, s22, v50
	s_waitcnt lgkmcnt(0)
	s_barrier
	ds_read_b128 v[82:85], v52
	ds_read_b128 v[94:97], v52 offset:64
	s_waitcnt vmcnt(7)
	v_cndmask_b32_e64 v77, 0, v77, s[12:13]
	v_cndmask_b32_e64 v76, 0, v76, s[12:13]
	v_cndmask_b32_e64 v75, 0, v75, s[12:13]
	v_cndmask_b32_e64 v74, 0, v74, s[12:13]
	s_waitcnt vmcnt(5)
	v_cndmask_b32_e64 v72, 0, v222, s[0:1]
	v_cndmask_b32_e64 v73, 0, v223, s[0:1]
	v_cndmask_b32_e64 v71, 0, v221, s[0:1]
	v_cndmask_b32_e64 v70, 0, v220, s[0:1]
	s_waitcnt lgkmcnt(1)
	v_mfma_f32_16x16x32_bf16 v[90:93], v[82:85], v[74:77], 0
	v_cndmask_b32_e64 v85, 0, v81, s[12:13]
	v_cndmask_b32_e64 v84, 0, v80, s[12:13]
	v_cndmask_b32_e64 v83, 0, v79, s[12:13]
	v_cndmask_b32_e64 v82, 0, v78, s[12:13]
	s_waitcnt lgkmcnt(0)
	s_nop 0
	v_mfma_f32_16x16x32_bf16 v[78:81], v[94:97], v[82:85], v[90:93]
	ds_read_b128 v[94:97], v52 offset:2304
	v_cndmask_b32_e64 v52, 0, 1, s[66:67]
	v_cmp_ne_u32_e64 s[76:77], 1, v52
	s_waitcnt lgkmcnt(0)
	v_mfma_f32_16x16x32_bf16 v[90:93], v[94:97], v[74:77], 0
	s_cbranch_vccnz .LBB0_1250
	v_mfma_f32_16x16x32_bf16 v[110:113], v[94:97], v[70:73], 0

.LBB0_1683:
	s_or_b64 exec, exec, s[6:7]
	v_add_u32_e32 v0, s10, v173
	v_cmp_lt_i32_e32 vcc, -1, v0
	s_and_saveexec_b64 s[6:7], vcc
	s_cbranch_execz .LBB0_1687
	v_lshlrev_b64 v[84:85], 12, v[0:1]
	v_lshl_add_u64 v[84:85], v[96:97], 0, v[84:85]
	global_load_dwordx2 v[88:89], v[84:85], off
	global_load_dwordx2 v[98:99], v[84:85], off offset:512
	global_load_dwordx2 v[102:103], v[84:85], off offset:1024
	global_load_dwordx2 v[106:107], v[84:85], off offset:1536
	global_load_dwordx2 v[110:111], v[84:85], off offset:2048
	global_load_dwordx2 v[114:115], v[84:85], off offset:2560
	global_load_dwordx2 v[118:119], v[84:85], off offset:3072
	global_load_dwordx2 v[182:183], v[84:85], off offset:3584
	v_cmp_gt_u32_e32 vcc, s5, v0
	s_and_saveexec_b64 s[8:9], vcc
	s_cbranch_execz .LBB0_1686
	v_lshlrev_b64 v[68:69], 11, v[0:1]
	v_lshl_add_u64 v[82:83], v[68:69], 1, v[94:95]
	global_load_dwordx2 v[68:69], v[82:83], off nt
	global_load_dwordx2 v[70:71], v[82:83], off offset:512 nt
	global_load_dwordx2 v[72:73], v[82:83], off offset:1024 nt
	global_load_dwordx2 v[74:75], v[82:83], off offset:1536 nt
	global_load_dwordx2 v[76:77], v[82:83], off offset:2048 nt
	global_load_dwordx2 v[78:79], v[82:83], off offset:2560 nt
	global_load_dwordx2 v[80:81], v[82:83], off offset:3072 nt
	s_nop 0
	global_load_dwordx2 v[82:83], v[82:83], off offset:3584 nt

.LBB0_1687:
	s_or_b64 exec, exec, s[6:7]
	v_pk_add_f32 v[162:163], v[140:141], v[152:153]
	v_pk_add_f32 v[164:165], v[138:139], v[146:147]
	v_add_f32_e32 v135, v132, v133
	v_pk_add_f32 v[162:163], v[162:163], v[164:165]
	v_add_f32_e32 v161, v124, v125
	v_add_f32_e32 v0, 0, v163
	v_add_f32_e32 v155, v162, v0
	v_pk_add_f32 v[162:163], v[156:157], v[122:123]
	v_pk_add_f32 v[164:165], v[134:135], v[160:161]
	v_pk_add_f32 v[162:163], v[162:163], v[162:163] op_sel_hi:[0,1]
	s_waitcnt lgkmcnt(0)
	v_mov_b32_e32 v127, v163
	v_pk_add_f32 v[162:163], v[126:127], v[154:155]
	v_add_f32_e32 v145, v136, v137
	v_pk_add_f32 v[162:163], v[164:165], v[162:163]
	v_pk_add_f32 v[164:165], v[150:151], v[128:129]
	v_pk_add_f32 v[162:163], v[162:163], v[162:163] op_sel_hi:[0,1]
	v_pk_add_f32 v[164:165], v[164:165], v[164:165] op_sel_hi:[0,1]
	v_add_f32_e32 v159, v130, v131
	v_mov_b32_e32 v143, v165
	v_mov_b32_e32 v149, v163
	v_pk_add_f32 v[174:175], v[144:145], v[158:159]
	v_pk_add_f32 v[162:163], v[142:143], v[148:149]
	v_cmp_lt_u32_e32 vcc, s19, v173
	v_pk_add_f32 v[162:163], v[174:175], v[162:163]
	s_nop 0
	v_add_f32_e32 v0, v162, v163
	ds_bpermute_b32 v67, v166, v0
	s_waitcnt lgkmcnt(0)
	v_add_f32_e32 v0, v0, v67
	ds_bpermute_b32 v67, v167, v0
	s_waitcnt lgkmcnt(0)
	v_add_f32_e32 v0, v0, v67
	ds_bpermute_b32 v67, v168, v0
	s_waitcnt lgkmcnt(0)
	v_add_f32_e32 v0, v0, v67
	ds_bpermute_b32 v67, v169, v0
	s_waitcnt lgkmcnt(0)
	v_add_f32_e32 v0, v0, v67
	ds_bpermute_b32 v67, v170, v0
	s_waitcnt lgkmcnt(0)
	v_add_f32_e32 v0, v0, v67
	ds_bpermute_b32 v67, v171, v0
	s_waitcnt lgkmcnt(0)
	v_add_f32_e32 v67, v0, v67
	v_fmac_f32_e32 v153, 0xba000000, v67
	v_fmac_f32_e32 v152, 0xba000000, v67
	v_fmac_f32_e32 v141, 0xba000000, v67
	v_fmac_f32_e32 v140, 0xba000000, v67
	v_mov_b32_e32 v164, v153
	v_mov_b32_e32 v165, v152
	v_fmac_f32_e32 v147, 0xba000000, v67
	v_fmac_f32_e32 v146, 0xba000000, v67
	v_mov_b32_e32 v162, v141
	v_mov_b32_e32 v163, v140
	v_pk_mul_f32 v[164:165], v[164:165], v[164:165]
	v_fmac_f32_e32 v139, 0xba000000, v67
	v_fmac_f32_e32 v138, 0xba000000, v67
	v_pk_fma_f32 v[162:163], v[162:163], v[162:163], v[164:165]
	v_mov_b32_e32 v164, v147
	v_mov_b32_e32 v165, v146
	v_mov_b32_e32 v174, v139
	v_mov_b32_e32 v175, v138
	v_pk_mul_f32 v[164:165], v[164:165], v[164:165]
	v_fmac_f32_e32 v123, 0xba000000, v67
	v_pk_fma_f32 v[164:165], v[174:175], v[174:175], v[164:165]
	v_fmac_f32_e32 v157, 0xba000000, v67
	v_fmac_f32_e32 v156, 0xba000000, v67
	v_fmac_f32_e32 v122, 0xba000000, v67
	v_pk_add_f32 v[162:163], v[162:163], v[164:165]
	v_mov_b32_e32 v164, v157
	v_mov_b32_e32 v165, v123
	v_mov_b32_e32 v174, v122
	v_mov_b32_e32 v175, v156
	v_pk_mul_f32 v[164:165], v[164:165], v[164:165]
	v_pk_mul_f32 v[174:175], v[174:175], v[174:175]
	v_fmac_f32_e32 v132, 0xba000000, v67
	v_pk_mov_b32 v[176:177], v[174:175], v[164:165] op_sel:[1,0]
	v_mov_b32_e32 v175, v165
	v_fmac_f32_e32 v124, 0xba000000, v67
	v_fmac_f32_e32 v133, 0xba000000, v67
	v_mul_f32_e32 v0, v132, v132
	v_pk_add_f32 v[164:165], v[176:177], v[174:175]
	v_fmac_f32_e32 v125, 0xba000000, v67
	v_pk_fma_f32 v[174:175], v[132:133], v[132:133], v[0:1] op_sel_hi:[1,1,0]
	v_mul_f32_e32 v0, v124, v124
	v_pk_add_f32 v[162:163], v[162:163], v[162:163] op_sel_hi:[0,1]
	v_pk_add_f32 v[164:165], v[164:165], v[164:165] op_sel_hi:[0,1]
	v_pk_fma_f32 v[176:177], v[124:125], v[124:125], v[0:1] op_sel_hi:[1,1,0]
	v_fmac_f32_e32 v154, 0xba000000, v67
	v_fmac_f32_e32 v126, 0xba000000, v67
	v_fmac_f32_e32 v160, 0xba000000, v67
	v_fmac_f32_e32 v134, 0xba000000, v67
	v_mul_f32_e32 v174, v134, v134
	v_mul_f32_e32 v176, v160, v160
	v_mul_f32_e32 v164, v126, v126
	v_mul_f32_e32 v162, v154, v154
	v_pk_add_f32 v[174:175], v[174:175], v[176:177]
	v_pk_add_f32 v[162:163], v[164:165], v[162:163]
	v_fmac_f32_e32 v129, 0xba000000, v67
	v_fmac_f32_e32 v151, 0xba000000, v67
	v_fmac_f32_e32 v150, 0xba000000, v67
	v_fmac_f32_e32 v128, 0xba000000, v67
	v_pk_add_f32 v[162:163], v[174:175], v[162:163]
	v_mov_b32_e32 v164, v151
	v_mov_b32_e32 v165, v129
	v_mov_b32_e32 v174, v128
	v_mov_b32_e32 v175, v150
	v_pk_mul_f32 v[164:165], v[164:165], v[164:165]
	v_pk_mul_f32 v[174:175], v[174:175], v[174:175]
	v_fmac_f32_e32 v136, 0xba000000, v67
	v_pk_mov_b32 v[176:177], v[174:175], v[164:165] op_sel:[1,0]
	v_mov_b32_e32 v175, v165
	v_fmac_f32_e32 v130, 0xba000000, v67
	v_fmac_f32_e32 v137, 0xba000000, v67
	v_mul_f32_e32 v0, v136, v136
	v_pk_add_f32 v[164:165], v[176:177], v[174:175]
	v_fmac_f32_e32 v131, 0xba000000, v67
	v_pk_fma_f32 v[174:175], v[136:137], v[136:137], v[0:1] op_sel_hi:[1,1,0]
	v_mul_f32_e32 v0, v130, v130
	v_pk_add_f32 v[162:163], v[162:163], v[162:163] op_sel_hi:[0,1]
	v_pk_add_f32 v[164:165], v[164:165], v[164:165] op_sel_hi:[0,1]
	v_pk_fma_f32 v[176:177], v[130:131], v[130:131], v[0:1] op_sel_hi:[1,1,0]
	v_fmac_f32_e32 v148, 0xba000000, v67
	v_fmac_f32_e32 v142, 0xba000000, v67
	v_fmac_f32_e32 v158, 0xba000000, v67
	v_fmac_f32_e32 v144, 0xba000000, v67
	v_mul_f32_e32 v174, v144, v144
	v_mul_f32_e32 v176, v158, v158
	v_mul_f32_e32 v164, v142, v142
	v_mul_f32_e32 v162, v148, v148
	v_pk_add_f32 v[174:175], v[174:175], v[176:177]
	v_pk_add_f32 v[162:163], v[164:165], v[162:163]
	s_nop 0
	v_pk_add_f32 v[162:163], v[174:175], v[162:163]
	s_nop 0
	v_add_f32_e32 v0, v162, v163
	ds_bpermute_b32 v67, v166, v0
	s_waitcnt lgkmcnt(0)
	v_add_f32_e32 v0, v0, v67
	ds_bpermute_b32 v67, v167, v0
	s_waitcnt lgkmcnt(0)
	v_add_f32_e32 v0, v0, v67
	ds_bpermute_b32 v67, v168, v0
	s_waitcnt lgkmcnt(0)
	v_add_f32_e32 v0, v0, v67
	ds_bpermute_b32 v67, v169, v0
	s_waitcnt lgkmcnt(0)
	v_add_f32_e32 v0, v0, v67
	ds_bpermute_b32 v67, v170, v0
	s_waitcnt lgkmcnt(0)
	v_add_f32_e32 v67, v0, v67
	ds_bpermute_b32 v127, v171, v67
	s_waitcnt vmcnt(7)
	v_and_b32_e32 v85, 0xffff0000, v89
	v_and_b32_e32 v87, 0xffff0000, v88
	v_lshlrev_b32_e32 v86, 16, v88
	v_lshlrev_b32_e32 v84, 16, v89
	s_waitcnt vmcnt(6)
	v_and_b32_e32 v89, 0xffff0000, v99
	v_and_b32_e32 v91, 0xffff0000, v98
	v_lshlrev_b32_e32 v90, 16, v98
	v_lshlrev_b32_e32 v88, 16, v99
	s_waitcnt vmcnt(5)
	v_and_b32_e32 v99, 0xffff0000, v103
	v_and_b32_e32 v101, 0xffff0000, v102
	v_lshlrev_b32_e32 v100, 16, v102
	v_lshlrev_b32_e32 v98, 16, v103
	s_waitcnt vmcnt(4)
	v_and_b32_e32 v103, 0xffff0000, v107
	v_and_b32_e32 v105, 0xffff0000, v106
	v_lshlrev_b32_e32 v104, 16, v106
	v_lshlrev_b32_e32 v102, 16, v107
	s_waitcnt vmcnt(3)
	v_and_b32_e32 v107, 0xffff0000, v111
	v_and_b32_e32 v109, 0xffff0000, v110
	v_lshlrev_b32_e32 v108, 16, v110
	v_lshlrev_b32_e32 v106, 16, v111
	s_waitcnt vmcnt(2)
	v_and_b32_e32 v111, 0xffff0000, v115
	v_and_b32_e32 v113, 0xffff0000, v114
	v_lshlrev_b32_e32 v112, 16, v114
	v_lshlrev_b32_e32 v110, 16, v115
	s_waitcnt vmcnt(1)
	v_and_b32_e32 v115, 0xffff0000, v119
	v_and_b32_e32 v117, 0xffff0000, v118
	v_lshlrev_b32_e32 v116, 16, v118
	v_lshlrev_b32_e32 v114, 16, v119
	s_waitcnt vmcnt(0)
	v_and_b32_e32 v119, 0xffff0000, v183
	v_and_b32_e32 v121, 0xffff0000, v182
	v_lshlrev_b32_e32 v120, 16, v182
	v_lshlrev_b32_e32 v118, 16, v183
	s_and_saveexec_b64 s[6:7], vcc
	s_xor_b64 s[6:7], exec, s[6:7]
	s_cbranch_execz .LBB0_1690
	v_add_u32_e32 v0, 0xffffdfc0, v173
	v_lshlrev_b64 v[162:163], 13, v[0:1]
	v_lshl_add_u64 v[162:163], s[0:1], 0, v[162:163]
	s_andn2_saveexec_b64 s[6:7], s[6:7]
	s_cbranch_execnz .LBB0_1691
